# natten full steps: gate loads issued before the K/V/q prefetch so the in-order gate waits (vmcnt 11/10/9/9) do not drain the prefetch; prefetch drained just before its LDS commit barrier
# baseline (speedup 1.0000x reference)
.LBB0_470:
	s_waitcnt vmcnt(2)
	v_med3_u32 v24, s80, 1, 57
	s_min_u32 s66, s80, 53
	v_readfirstlane_b32 s67, v24
	s_sub_i32 s69, s66, s67
	s_add_i32 s87, s67, 7
	s_add_i32 s88, s69, 4
	s_cmp_eq_u32 s69, 0
	s_cselect_b32 s98, 1, 0
	s_cmp_lg_u32 s34, 0x78000
	s_cselect_b32 s98, s98, 0
	s_cmp_eq_u32 s98, 0
	s_cbranch_scc1 .Lng_noearly
	v_lshl_add_u64 v[210:211], v[126:127], 0, s[34:35]
	global_load_dwordx2 v[190:191], v[210:211], off offset:-64
	global_load_dwordx2 v[192:193], v[210:211], off offset:-32
	global_load_dwordx2 v[198:199], v[210:211], off
	global_load_dwordx2 v[200:201], v[210:211], off offset:32
.Lng_noearly:
	s_cmp_gt_i32 s69, -4
	s_cselect_b64 s[66:67], -1, 0
	s_cmp_lt_i32 s69, -3
	v_cmp_gt_i32_e32 vcc, s88, v145
	s_cbranch_scc1 .LBB0_480
	s_lshl_b32 s69, s87, 13
	s_add_u32 s70, s20, s69
	s_addc_u32 s71, s21, 0
	s_and_saveexec_b64 s[82:83], vcc
	s_cbranch_execz .LBB0_473
	v_lshl_add_u64 v[12:13], s[70:71], 0, v[188:189]
	global_load_dwordx4 v[12:15], v[12:13], off

.LBB0_482:
	s_cmp_lg_u32 s98, 0
	s_cbranch_scc1 .Lng_skiplate
	v_lshl_add_u64 v[210:211], v[126:127], 0, s[34:35]
	global_load_dwordx2 v[190:191], v[210:211], off offset:-64
	global_load_dwordx2 v[192:193], v[210:211], off offset:-32
	global_load_dwordx2 v[198:199], v[210:211], off
	global_load_dwordx2 v[200:201], v[210:211], off offset:32

.LBB0_483:
	s_mulk_i32 s69, 0x60
	v_add_u32_e32 v179, s69, v177
	s_mulk_i32 s70, 0x60
	v_add_u32_e32 v194, s69, v178
	ds_read_b64 v[180:181], v179
	ds_read_b64 v[184:185], v179 offset:17152
	ds_read_b64 v[202:203], v179 offset:34304
	ds_read_b64 v[216:217], v179 offset:51456
	ds_read_b64 v[182:183], v194
	ds_read_b64 v[186:187], v194 offset:17152
	ds_read_b64 v[204:205], v194 offset:34304
	ds_read_b64 v[218:219], v194 offset:51456
	v_add_u32_e32 v179, s70, v177
	v_add_u32_e32 v194, s70, v178
	ds_read_b64 v[220:221], v179
	ds_read_b64 v[224:225], v179 offset:17152
	ds_read_b64 v[228:229], v179 offset:34304
	ds_read_b64 v[232:233], v179 offset:51456
	ds_read_b64 v[222:223], v194
	ds_read_b64 v[226:227], v194 offset:17152
	ds_read_b64 v[230:231], v194 offset:34304
	ds_read_b64 v[234:235], v194 offset:51456
	v_exp_f32_e32 v44, v44
	v_exp_f32_e32 v40, v40
	v_exp_f32_e32 v45, v45
	v_exp_f32_e32 v41, v41
	v_exp_f32_e32 v46, v46
	v_exp_f32_e32 v47, v47
	v_exp_f32_e32 v42, v42
	v_exp_f32_e32 v43, v43
	v_cvt_pk_bf16_f32 v44, v44, v45
	v_cvt_pk_bf16_f32 v45, v46, v47
	v_cvt_pk_bf16_f32 v46, v40, v41
	v_cvt_pk_bf16_f32 v47, v42, v43
	s_waitcnt lgkmcnt(11)
	s_nop 0
	v_mfma_f32_16x16x32_bf16 v[180:183], v[180:183], v[44:47], 0
	s_waitcnt lgkmcnt(10)
	v_mfma_f32_16x16x32_bf16 v[184:187], v[184:187], v[44:47], 0
	s_waitcnt lgkmcnt(9)
	v_mfma_f32_16x16x32_bf16 v[202:205], v[202:205], v[44:47], 0
	s_waitcnt lgkmcnt(8)
	v_mfma_f32_16x16x32_bf16 v[216:219], v[216:219], v[44:47], 0
	s_mulk_i32 s82, 0x60
	v_add_u32_e32 v179, s82, v177
	v_add_u32_e32 v196, s82, v178
	ds_read_b64 v[236:237], v179
	ds_read_b64 v[240:241], v179 offset:17152
	ds_read_b64 v[244:245], v179 offset:34304
	ds_read_b64 v[194:195], v179 offset:51456
	ds_read_b64 v[238:239], v196
	ds_read_b64 v[242:243], v196 offset:17152
	ds_read_b64 v[246:247], v196 offset:34304
	ds_read_b64 v[196:197], v196 offset:51456
	s_mov_b32 s26, s24
	s_mov_b32 s27, s24
	s_mov_b32 s25, s24
	v_mov_b64_e32 v[42:43], s[26:27]
	v_mov_b64_e32 v[40:41], s[24:25]
	v_exp_f32_e32 v36, v36
	v_exp_f32_e32 v179, v32
	v_exp_f32_e32 v32, v37
	v_exp_f32_e32 v37, v33
	v_exp_f32_e32 v33, v38
	v_exp_f32_e32 v38, v39
	v_exp_f32_e32 v39, v34
	v_exp_f32_e32 v35, v35
	v_mfma_f32_16x16x32_bf16 v[44:47], v[40:43], v[44:47], 0
	v_cvt_pk_bf16_f32 v32, v36, v32
	v_cvt_pk_bf16_f32 v33, v33, v38
	v_cvt_pk_bf16_f32 v34, v179, v37
	v_cvt_pk_bf16_f32 v35, v39, v35
	s_waitcnt lgkmcnt(11)
	s_nop 0
	v_mfma_f32_16x16x32_bf16 v[36:39], v[220:223], v[32:35], v[180:183]
	s_waitcnt lgkmcnt(10)
	v_mfma_f32_16x16x32_bf16 v[180:183], v[224:227], v[32:35], v[184:187]
	s_waitcnt lgkmcnt(9)
	v_mfma_f32_16x16x32_bf16 v[184:187], v[228:231], v[32:35], v[202:205]
	s_waitcnt lgkmcnt(8)
	v_mfma_f32_16x16x32_bf16 v[202:205], v[232:235], v[32:35], v[216:219]
	s_mulk_i32 s83, 0x60
	v_add_u32_e32 v179, s83, v177
	v_mfma_f32_16x16x32_bf16 v[32:35], v[40:43], v[32:35], v[44:47]
	v_add_u32_e32 v215, s83, v178
	s_nop 1
	ds_read_b64 v[44:45], v179
	ds_read_b64 v[216:217], v179 offset:17152
	ds_read_b64 v[220:221], v179 offset:34304
	ds_read_b64 v[224:225], v179 offset:51456
	ds_read_b64 v[46:47], v215
	ds_read_b64 v[218:219], v215 offset:17152
	ds_read_b64 v[222:223], v215 offset:34304
	ds_read_b64 v[226:227], v215 offset:51456
	v_exp_f32_e32 v52, v52
	v_exp_f32_e32 v179, v48
	v_exp_f32_e32 v48, v53
	v_exp_f32_e32 v53, v49
	v_exp_f32_e32 v49, v54
	v_exp_f32_e32 v54, v55
	v_exp_f32_e32 v55, v50
	v_exp_f32_e32 v51, v51
	v_cvt_pk_bf16_f32 v48, v52, v48
	v_cvt_pk_bf16_f32 v49, v49, v54
	v_cvt_pk_bf16_f32 v50, v179, v53
	v_cvt_pk_bf16_f32 v51, v55, v51
	s_waitcnt lgkmcnt(11)
	s_nop 0
	v_mfma_f32_16x16x32_bf16 v[36:39], v[236:239], v[48:51], v[36:39]
	s_waitcnt lgkmcnt(10)
	v_mfma_f32_16x16x32_bf16 v[52:55], v[240:243], v[48:51], v[180:183]
	s_waitcnt lgkmcnt(9)
	v_mfma_f32_16x16x32_bf16 v[180:183], v[244:247], v[48:51], v[184:187]
	s_waitcnt lgkmcnt(8)
	v_mfma_f32_16x16x32_bf16 v[184:187], v[194:197], v[48:51], v[202:205]
	s_mulk_i32 s84, 0x60
	v_add_u32_e32 v179, s84, v177
	v_mfma_f32_16x16x32_bf16 v[32:35], v[40:43], v[48:51], v[32:35]
	v_add_u32_e32 v215, s84, v178
	ds_read_b64 v[48:49], v179
	ds_read_b64 v[194:195], v179 offset:17152
	ds_read_b64 v[202:203], v179 offset:34304
	ds_read_b64 v[228:229], v179 offset:51456
	ds_read_b64 v[50:51], v215
	ds_read_b64 v[196:197], v215 offset:17152
	ds_read_b64 v[204:205], v215 offset:34304
	ds_read_b64 v[230:231], v215 offset:51456
	v_exp_f32_e32 v60, v60
	v_exp_f32_e32 v179, v56
	v_exp_f32_e32 v56, v61
	v_exp_f32_e32 v61, v57
	v_exp_f32_e32 v57, v62
	v_exp_f32_e32 v62, v63
	v_exp_f32_e32 v63, v58
	v_exp_f32_e32 v59, v59
	v_cvt_pk_bf16_f32 v56, v60, v56
	v_cvt_pk_bf16_f32 v57, v57, v62
	v_cvt_pk_bf16_f32 v58, v179, v61
	v_cvt_pk_bf16_f32 v59, v63, v59
	s_waitcnt lgkmcnt(11)
	s_nop 0
	v_mfma_f32_16x16x32_bf16 v[36:39], v[44:47], v[56:59], v[36:39]
	s_waitcnt lgkmcnt(10)
	v_mfma_f32_16x16x32_bf16 v[44:47], v[216:219], v[56:59], v[52:55]
	s_waitcnt lgkmcnt(9)
	v_mfma_f32_16x16x32_bf16 v[52:55], v[220:223], v[56:59], v[180:183]
	s_waitcnt lgkmcnt(8)
	v_mfma_f32_16x16x32_bf16 v[60:63], v[224:227], v[56:59], v[184:187]
	s_mulk_i32 s85, 0x60
	v_add_u32_e32 v179, s85, v177
	v_mfma_f32_16x16x32_bf16 v[32:35], v[40:43], v[56:59], v[32:35]
	v_add_u32_e32 v215, s85, v178
	ds_read_b64 v[56:57], v179
	ds_read_b64 v[180:181], v179 offset:17152
	ds_read_b64 v[184:185], v179 offset:34304
	ds_read_b64 v[216:217], v179 offset:51456
	ds_read_b64 v[58:59], v215
	ds_read_b64 v[182:183], v215 offset:17152
	ds_read_b64 v[186:187], v215 offset:34304
	ds_read_b64 v[218:219], v215 offset:51456
	v_exp_f32_e32 v68, v68
	v_exp_f32_e32 v179, v64
	v_exp_f32_e32 v64, v69
	v_exp_f32_e32 v69, v65
	v_exp_f32_e32 v65, v70
	v_exp_f32_e32 v70, v71
	v_exp_f32_e32 v71, v66
	v_exp_f32_e32 v67, v67
	v_cvt_pk_bf16_f32 v64, v68, v64
	v_cvt_pk_bf16_f32 v65, v65, v70
	v_cvt_pk_bf16_f32 v66, v179, v69
	v_cvt_pk_bf16_f32 v67, v71, v67
	s_waitcnt lgkmcnt(11)
	s_nop 0
	v_mfma_f32_16x16x32_bf16 v[36:39], v[48:51], v[64:67], v[36:39]
	s_waitcnt lgkmcnt(10)
	v_mfma_f32_16x16x32_bf16 v[44:47], v[194:197], v[64:67], v[44:47]
	s_waitcnt lgkmcnt(9)
	v_mfma_f32_16x16x32_bf16 v[48:51], v[202:205], v[64:67], v[52:55]
	s_waitcnt lgkmcnt(8)
	v_mfma_f32_16x16x32_bf16 v[52:55], v[228:231], v[64:67], v[60:63]
	s_mulk_i32 s89, 0x60
	s_nop 1
	v_add_u32_e32 v62, s89, v177
	v_mfma_f32_16x16x32_bf16 v[32:35], v[40:43], v[64:67], v[32:35]
	v_add_u32_e32 v179, s89, v178
	ds_read_b64 v[60:61], v62
	ds_read_b64 v[64:65], v62 offset:17152
	ds_read_b64 v[68:69], v62 offset:34304
	ds_read_b64 v[194:195], v62 offset:51456
	ds_read_b64 v[62:63], v179
	ds_read_b64 v[66:67], v179 offset:17152
	ds_read_b64 v[70:71], v179 offset:34304
	ds_read_b64 v[196:197], v179 offset:51456
	v_exp_f32_e32 v76, v76
	v_exp_f32_e32 v179, v72
	v_exp_f32_e32 v72, v77
	v_exp_f32_e32 v77, v73
	v_exp_f32_e32 v73, v78
	v_exp_f32_e32 v78, v79
	v_exp_f32_e32 v79, v74
	v_exp_f32_e32 v75, v75
	v_cvt_pk_bf16_f32 v72, v76, v72
	v_cvt_pk_bf16_f32 v73, v73, v78
	v_cvt_pk_bf16_f32 v74, v179, v77
	v_cvt_pk_bf16_f32 v75, v79, v75
	s_waitcnt lgkmcnt(11)
	s_nop 0
	v_mfma_f32_16x16x32_bf16 v[36:39], v[56:59], v[72:75], v[36:39]
	s_waitcnt lgkmcnt(10)
	v_mfma_f32_16x16x32_bf16 v[44:47], v[180:183], v[72:75], v[44:47]
	s_waitcnt lgkmcnt(9)
	v_mfma_f32_16x16x32_bf16 v[48:51], v[184:187], v[72:75], v[48:51]
	s_waitcnt lgkmcnt(8)
	v_mfma_f32_16x16x32_bf16 v[52:55], v[216:219], v[72:75], v[52:55]
	s_mulk_i32 s94, 0x60
	v_add_u32_e32 v58, s94, v177
	v_mfma_f32_16x16x32_bf16 v[32:35], v[40:43], v[72:75], v[32:35]
	v_add_u32_e32 v179, s94, v178
	ds_read_b64 v[56:57], v58
	ds_read_b64 v[72:73], v58 offset:17152
	ds_read_b64 v[76:77], v58 offset:34304
	ds_read_b64 v[180:181], v58 offset:51456
	ds_read_b64 v[58:59], v179
	ds_read_b64 v[74:75], v179 offset:17152
	ds_read_b64 v[78:79], v179 offset:34304
	ds_read_b64 v[182:183], v179 offset:51456
	v_exp_f32_e32 v92, v92
	v_exp_f32_e32 v179, v88
	v_exp_f32_e32 v88, v93
	v_exp_f32_e32 v93, v89
	v_exp_f32_e32 v89, v94
	v_exp_f32_e32 v94, v95
	v_exp_f32_e32 v95, v90
	v_exp_f32_e32 v91, v91
	v_cvt_pk_bf16_f32 v88, v92, v88
	v_cvt_pk_bf16_f32 v89, v89, v94
	v_cvt_pk_bf16_f32 v90, v179, v93
	v_cvt_pk_bf16_f32 v91, v95, v91
	s_waitcnt lgkmcnt(11)
	s_nop 0
	v_mfma_f32_16x16x32_bf16 v[36:39], v[60:63], v[88:91], v[36:39]
	s_waitcnt lgkmcnt(10)
	v_mfma_f32_16x16x32_bf16 v[44:47], v[64:67], v[88:91], v[44:47]
	s_waitcnt lgkmcnt(9)
	v_mfma_f32_16x16x32_bf16 v[48:51], v[68:71], v[88:91], v[48:51]
	s_waitcnt lgkmcnt(8)
	v_mfma_f32_16x16x32_bf16 v[52:55], v[194:197], v[88:91], v[52:55]
	v_exp_f32_e32 v64, v96
	v_exp_f32_e32 v66, v80
	v_mfma_f32_16x16x32_bf16 v[60:63], v[40:43], v[88:91], v[32:35]
	v_exp_f32_e32 v67, v82
	v_exp_f32_e32 v68, v83
	s_nop 0
	v_exp_f32_e32 v32, v97
	v_exp_f32_e32 v33, v81
	v_exp_f32_e32 v34, v98
	v_exp_f32_e32 v35, v99
	v_cvt_pk_bf16_f32 v64, v64, v32
	v_cvt_pk_bf16_f32 v66, v66, v33
	v_cvt_pk_bf16_f32 v67, v67, v68
	v_cvt_pk_bf16_f32 v65, v34, v35
	s_waitcnt lgkmcnt(3)
	s_nop 0
	v_mfma_f32_16x16x32_bf16 v[36:39], v[56:59], v[64:67], v[36:39]
	s_waitcnt lgkmcnt(2)
	v_mfma_f32_16x16x32_bf16 v[56:59], v[72:75], v[64:67], v[44:47]
	s_waitcnt lgkmcnt(1)
	v_mfma_f32_16x16x32_bf16 v[44:47], v[76:79], v[64:67], v[48:51]
	s_waitcnt lgkmcnt(0)
	v_mfma_f32_16x16x32_bf16 v[32:35], v[180:183], v[64:67], v[52:55]
	v_mfma_f32_16x16x32_bf16 v[40:43], v[40:43], v[64:67], v[60:63]
	s_andn2_b64 vcc, exec, s[66:67]
	s_cmp_lg_u32 s98, 0
	s_cbranch_scc1 .Lng_wf0
	s_waitcnt vmcnt(3)
	s_branch .Lng_wj0
.Lng_wf0:
	s_waitcnt vmcnt(11)
.Lng_wj0:
	s_nop 5
	v_lshlrev_b32_e32 v42, 16, v190
	v_mul_f32_e32 v41, 0xbfb8aa3b, v42
	v_exp_f32_e32 v41, v41
	v_rcp_f32_e32 v40, v40
	v_and_b32_e32 v43, 0xffff0000, v190
	v_add_f32_e32 v41, 1.0, v41
	v_rcp_f32_e32 v48, v41
	v_pk_mul_f32 v[36:37], v[36:37], v[40:41] op_sel_hi:[1,0]
	v_mul_f32_e32 v41, 0xbfb8aa3b, v43
	v_exp_f32_e32 v41, v41
	s_nop 0
	v_add_f32_e32 v41, 1.0, v41
	v_rcp_f32_e32 v49, v41
	v_pk_mul_f32 v[38:39], v[38:39], v[40:41] op_sel_hi:[1,0]
	v_pk_mul_f32 v[42:43], v[48:49], v[42:43]
	s_nop 0
	v_pk_mul_f32 v[36:37], v[42:43], v[36:37]
	v_lshlrev_b32_e32 v42, 16, v191
	v_cvt_pk_bf16_f32 v36, v36, v37
	v_mul_f32_e32 v37, 0xbfb8aa3b, v42
	v_exp_f32_e32 v37, v37
	v_and_b32_e32 v43, 0xffff0000, v191
	v_add_f32_e32 v37, 1.0, v37
	v_rcp_f32_e32 v48, v37
	v_mul_f32_e32 v37, 0xbfb8aa3b, v43
	v_exp_f32_e32 v37, v37
	s_nop 0
	v_add_f32_e32 v37, 1.0, v37
	v_rcp_f32_e32 v49, v37
	s_nop 0
	v_pk_mul_f32 v[42:43], v[48:49], v[42:43]
	s_nop 0
	v_pk_mul_f32 v[38:39], v[42:43], v[38:39]
	s_nop 0
	v_cvt_pk_bf16_f32 v37, v38, v39
	s_cmp_lg_u32 s98, 0
	s_cbranch_scc1 .Lng_wf1
	s_waitcnt vmcnt(2)
	s_branch .Lng_wj1
.Lng_wf1:
	s_waitcnt vmcnt(10)
.Lng_wj1:
	v_lshlrev_b32_e32 v38, 16, v192
	v_mul_f32_e32 v41, 0xbfb8aa3b, v38
	v_exp_f32_e32 v41, v41
	v_and_b32_e32 v39, 0xffff0000, v192
	v_add_f32_e32 v41, 1.0, v41
	v_rcp_f32_e32 v42, v41
	v_pk_mul_f32 v[48:49], v[56:57], v[40:41] op_sel_hi:[1,0]
	v_mul_f32_e32 v41, 0xbfb8aa3b, v39
	v_exp_f32_e32 v41, v41
	s_nop 0
	v_add_f32_e32 v41, 1.0, v41
	v_rcp_f32_e32 v43, v41
	v_pk_mul_f32 v[50:51], v[58:59], v[40:41] op_sel_hi:[1,0]
	v_pk_mul_f32 v[38:39], v[42:43], v[38:39]
	s_nop 0
	v_pk_mul_f32 v[38:39], v[38:39], v[48:49]
	v_lshlrev_b32_e32 v42, 16, v193
	v_cvt_pk_bf16_f32 v38, v38, v39
	v_mul_f32_e32 v39, 0xbfb8aa3b, v42
	v_exp_f32_e32 v39, v39
	v_and_b32_e32 v43, 0xffff0000, v193
	v_permlane16_swap_b32_e32 v36, v38
	v_add_f32_e32 v39, 1.0, v39
	v_rcp_f32_e32 v48, v39
	v_mul_f32_e32 v39, 0xbfb8aa3b, v43
	v_exp_f32_e32 v39, v39
	s_nop 0
	v_add_f32_e32 v39, 1.0, v39
	v_rcp_f32_e32 v49, v39
	s_nop 0
	v_pk_mul_f32 v[42:43], v[48:49], v[42:43]
	s_nop 0
	v_pk_mul_f32 v[42:43], v[42:43], v[50:51]
	s_nop 0
	v_cvt_pk_bf16_f32 v39, v42, v43
	s_cmp_lg_u32 s98, 0
	s_cbranch_scc1 .Lng_wf2
	s_waitcnt vmcnt(1)
	s_branch .Lng_wj2
.Lng_wf2:
	s_waitcnt vmcnt(9)
.Lng_wj2:
	v_lshlrev_b32_e32 v42, 16, v198
	v_mul_f32_e32 v41, 0xbfb8aa3b, v42
	v_exp_f32_e32 v41, v41
	v_and_b32_e32 v43, 0xffff0000, v198
	v_permlane16_swap_b32_e32 v37, v39
	v_add_f32_e32 v41, 1.0, v41
	v_rcp_f32_e32 v48, v41
	v_pk_mul_f32 v[44:45], v[44:45], v[40:41] op_sel_hi:[1,0]
	v_mul_f32_e32 v41, 0xbfb8aa3b, v43
	v_exp_f32_e32 v41, v41
	global_store_dwordx4 v[130:131], v[36:39], off
	v_add_f32_e32 v41, 1.0, v41
	v_rcp_f32_e32 v49, v41
	s_nop 0
	v_pk_mul_f32 v[42:43], v[48:49], v[42:43]
	s_nop 0
	v_pk_mul_f32 v[42:43], v[42:43], v[44:45]
	v_lshlrev_b32_e32 v44, 16, v199
	v_mul_f32_e32 v41, 0xbfb8aa3b, v44
	v_exp_f32_e32 v41, v41
	v_and_b32_e32 v45, 0xffff0000, v199
	v_cvt_pk_bf16_f32 v42, v42, v43
	v_add_f32_e32 v41, 1.0, v41
	v_rcp_f32_e32 v48, v41
	v_pk_mul_f32 v[46:47], v[46:47], v[40:41] op_sel_hi:[1,0]
	v_mul_f32_e32 v41, 0xbfb8aa3b, v45
	v_exp_f32_e32 v41, v41
	s_nop 0
	v_add_f32_e32 v41, 1.0, v41
	v_rcp_f32_e32 v49, v41
	s_nop 0
	v_pk_mul_f32 v[44:45], v[48:49], v[44:45]
	s_nop 0
	v_pk_mul_f32 v[44:45], v[44:45], v[46:47]
	s_nop 0
	v_cvt_pk_bf16_f32 v43, v44, v45
	s_cmp_lg_u32 s98, 0
	s_cbranch_scc1 .Lng_wf3
	s_waitcnt vmcnt(1)
	s_branch .Lng_wj3

.Lng_wj3:
	v_lshlrev_b32_e32 v44, 16, v200
	v_mul_f32_e32 v41, 0xbfb8aa3b, v44
	v_exp_f32_e32 v41, v41
	v_and_b32_e32 v45, 0xffff0000, v200
	v_add_f32_e32 v41, 1.0, v41
	v_rcp_f32_e32 v46, v41
	v_pk_mul_f32 v[32:33], v[32:33], v[40:41] op_sel_hi:[1,0]
	v_mul_f32_e32 v41, 0xbfb8aa3b, v45
	v_exp_f32_e32 v41, v41
	s_nop 0
	v_add_f32_e32 v41, 1.0, v41
	v_rcp_f32_e32 v47, v41
	s_nop 0
	v_pk_mul_f32 v[44:45], v[46:47], v[44:45]
	s_nop 0
	v_pk_mul_f32 v[32:33], v[44:45], v[32:33]
	s_nop 0
	v_cvt_pk_bf16_f32 v44, v32, v33
	v_lshlrev_b32_e32 v32, 16, v201
	v_mul_f32_e32 v41, 0xbfb8aa3b, v32
	v_exp_f32_e32 v41, v41
	v_and_b32_e32 v33, 0xffff0000, v201
	v_mov_b64_e32 v[190:191], 0x200
	v_mov_b64_e32 v[192:193], 0x1ff
	v_mov_b64_e32 v[198:199], 0x600
	v_mov_b64_e32 v[200:201], 0x5ff
	v_mov_b64_e32 v[210:211], 0x4ff
	v_permlane16_swap_b32_e32 v42, v44
	v_add_f32_e32 v41, 1.0, v41
	v_pk_mul_f32 v[34:35], v[34:35], v[40:41] op_sel_hi:[1,0]
	v_mul_f32_e32 v40, 0xbfb8aa3b, v33
	v_exp_f32_e32 v40, v40
	v_rcp_f32_e32 v46, v41
	v_add_f32_e32 v40, 1.0, v40
	v_rcp_f32_e32 v47, v40
	s_nop 0
	v_pk_mul_f32 v[32:33], v[46:47], v[32:33]
	s_nop 0
	v_pk_mul_f32 v[32:33], v[32:33], v[34:35]
	s_nop 0
	v_cvt_pk_bf16_f32 v45, v32, v33
	s_nop 1
	v_permlane16_swap_b32_e32 v43, v45
	global_store_dwordx4 v[128:129], v[42:45], off
	s_waitcnt vmcnt(2)
	s_waitcnt lgkmcnt(0)
	s_barrier
	s_cbranch_vccnz .LBB0_489
	v_cmp_gt_i32_e32 vcc, s88, v145
	s_and_saveexec_b64 s[66:67], vcc
	s_cbranch_execnz .LBB0_495
	s_or_b64 exec, exec, s[66:67]
	v_cmp_gt_i32_e32 vcc, s88, v146
	s_and_saveexec_b64 s[66:67], vcc
	s_cbranch_execnz .LBB0_496
